# P2/P6 residual epilogues: 2nd/3rd vmcnt(0) made counted (3/6 stores may stay in flight); retention chunk loop: redundant loop-top vmcnt waits removed (back-edge wait covers them), one full wait in pre
# speedup vs baseline: 1.0141x; 1.0036x over previous
; __device__ __forceinline__ unsigned cvt_pk_bf16(float lo, float hi) { unsigned r; asm volatile("v_cvt_pk_bf16_f32 %0, %1, %2" : "=v"(r) : "v"(lo), "v"(hi)); return r; }
;     __device__ __forceinline__ void operator()(const Acc& acc, const Unit& u, int wr, int wc, int fr, int fq) const {
;     ...
;                 for (int bj = 0; bj < 2; ++bj) {
;                     const f32x4 o0 = R[m][bj][0] + acc[ai][bj][m][0] * sc, o1 = R[m][bj][1] + acc[ai][bj][m][1] * sc;
;                     if (ok) {
;                         *(f32x4*)(dst + bj * 32) = o0; *(f32x4*)(dst + bj * 32 + 4) = o1;
;                         if (MODE != 2) { part += ((o0[0] * o0[0] + o0[1] * o0[1]) + (o0[2] * o0[2] + o0[3] * o0[3])) + ((o1[0] * o1[0] + o1[1] * o1[1]) + (o1[2] * o1[2] + o1[3] * o1[3]));
;                             u32x4 w; w.x = cvt_pk_bf16(o0[0], o0[1]); w.y = cvt_pk_bf16(o0[2], o0[3]); w.z = cvt_pk_bf16(o1[0], o1[1]); w.w = cvt_pk_bf16(o1[2], o1[3]);
;                             *(u32x4*)(xb + (size_t)row * DM + colb + bj * 32) = w; }
;                     }
;                 }
;                 if (MODE != 2) { part += __shfl_xor(part, 16); part += __shfl_xor(part, 32); if (ok && fq == 0) atomicAdd(ssn + row, part); }
.LBB0_553:
	s_or_b64 exec, exec, s[0:1]
	s_and_saveexec_b64 s[0:1], s[16:17]
	s_cbranch_execz .LBB0_555
	s_waitcnt vmcnt(3)
	v_pk_fma_f32 v[116:117], v[116:117], 0.5, v[180:181] op_sel_hi:[1,0,1]
	v_pk_fma_f32 v[112:113], v[112:113], 0.5, v[176:177] op_sel_hi:[1,0,1]
	v_pk_fma_f32 v[118:119], v[118:119], 0.5, v[182:183] op_sel_hi:[1,0,1]
	v_pk_fma_f32 v[114:115], v[114:115], 0.5, v[178:179] op_sel_hi:[1,0,1]
	v_mov_b32_e32 v122, v113
	v_mov_b32_e32 v123, v117
	v_mov_b32_e32 v120, v112
	v_mov_b32_e32 v121, v116
	v_pk_mul_f32 v[122:123], v[122:123], v[122:123]
	v_mov_b32_e32 v124, v115
	v_mov_b32_e32 v125, v119
	v_pk_fma_f32 v[120:121], v[120:121], v[120:121], v[122:123]
	v_mov_b32_e32 v122, v114
	v_mov_b32_e32 v123, v118
	v_pk_mul_f32 v[124:125], v[124:125], v[124:125]
	global_store_dwordx4 v[232:233], v[112:115], off offset:128 nt
	global_store_dwordx4 v[232:233], v[116:119], off offset:144 nt
	v_pk_fma_f32 v[122:123], v[122:123], v[122:123], v[124:125]
	v_cvt_pk_bf16_f32 v112, v112, v113
	v_cvt_pk_bf16_f32 v113, v114, v115
	v_cvt_pk_bf16_f32 v114, v116, v117
	v_cvt_pk_bf16_f32 v115, v118, v119
	global_store_dwordx4 v[230:231], v[112:115], off offset:64
	v_pk_add_f32 v[120:121], v[120:121], v[122:123]
	s_nop 0
	v_add_f32_e32 v120, v120, v121
	v_add_f32_e32 v219, v120, v219
.LBB0_555:
	s_or_b64 exec, exec, s[0:1]
	v_and_b32_e32 v113, 64, v241
	v_xor_b32_e32 v112, 16, v241
	v_add_u32_e32 v113, 64, v113
	v_cmp_lt_i32_e64 s[0:1], v112, v113
	v_xor_b32_e32 v114, 32, v241
	s_and_b64 s[2:3], s[4:5], s[16:17]
	v_cndmask_b32_e64 v112, v241, v112, s[0:1]
	s_waitcnt vmcnt(6)
	v_lshlrev_b32_e32 v176, 2, v112
	ds_bpermute_b32 v112, v176, v219
	v_cmp_lt_i32_e64 s[0:1], v114, v113
	s_waitcnt lgkmcnt(0)
	v_add_f32_e32 v112, v219, v112
	v_cndmask_b32_e64 v113, v241, v114, s[0:1]
	v_lshlrev_b32_e32 v177, 2, v113
	ds_bpermute_b32 v113, v177, v112
	s_and_saveexec_b64 s[0:1], s[2:3]
	s_cbranch_execz .LBB0_557
	v_lshl_add_u64 v[114:115], v[216:217], 2, s[28:29]
	s_waitcnt lgkmcnt(0)
	v_add_f32_e32 v112, v112, v113
	global_atomic_add_f32 v[114:115], v112, off

; __device__ __forceinline__ unsigned cvt_pk_bf16(float lo, float hi) { unsigned r; asm volatile("v_cvt_pk_bf16_f32 %0, %1, %2" : "=v"(r) : "v"(lo), "v"(hi)); return r; }
;     __device__ __forceinline__ void operator()(const Acc& acc, const Unit& u, int wr, int wc, int fr, int fq) const {
;     ...
;                 for (int bj = 0; bj < 2; ++bj) {
;                     const f32x4 o0 = R[m][bj][0] + acc[ai][bj][m][0] * sc, o1 = R[m][bj][1] + acc[ai][bj][m][1] * sc;
;                     if (ok) {
;                         *(f32x4*)(dst + bj * 32) = o0; *(f32x4*)(dst + bj * 32 + 4) = o1;
;                         if (MODE != 2) { part += ((o0[0] * o0[0] + o0[1] * o0[1]) + (o0[2] * o0[2] + o0[3] * o0[3])) + ((o1[0] * o1[0] + o1[1] * o1[1]) + (o1[2] * o1[2] + o1[3] * o1[3]));
;                             u32x4 w; w.x = cvt_pk_bf16(o0[0], o0[1]); w.y = cvt_pk_bf16(o0[2], o0[3]); w.z = cvt_pk_bf16(o1[0], o1[1]); w.w = cvt_pk_bf16(o1[2], o1[3]);
;                             *(u32x4*)(xb + (size_t)row * DM + colb + bj * 32) = w; }
;                     }
;                 }
;                 if (MODE != 2) { part += __shfl_xor(part, 16); part += __shfl_xor(part, 32); if (ok && fq == 0) atomicAdd(ssn + row, part); }
.LBB0_1603:
	s_or_b64 exec, exec, s[0:1]
	s_and_saveexec_b64 s[0:1], s[14:15]
	s_cbranch_execz .LBB0_1605
	s_waitcnt vmcnt(3)
	v_pk_add_f32 v[116:117], v[116:117], v[180:181]
	v_pk_add_f32 v[112:113], v[112:113], v[176:177]
	v_pk_add_f32 v[118:119], v[118:119], v[182:183]
	v_pk_add_f32 v[114:115], v[114:115], v[178:179]
	v_mov_b32_e32 v122, v113
	v_mov_b32_e32 v123, v117
	v_mov_b32_e32 v120, v112
	v_mov_b32_e32 v121, v116
	v_pk_mul_f32 v[122:123], v[122:123], v[122:123]
	v_mov_b32_e32 v124, v115
	v_mov_b32_e32 v125, v119
	v_pk_fma_f32 v[120:121], v[120:121], v[120:121], v[122:123]
	v_mov_b32_e32 v122, v114
	v_mov_b32_e32 v123, v118
	v_pk_mul_f32 v[124:125], v[124:125], v[124:125]
	global_store_dwordx4 v[224:225], v[112:115], off offset:128 nt
	global_store_dwordx4 v[224:225], v[116:119], off offset:144 nt
	v_pk_fma_f32 v[122:123], v[122:123], v[122:123], v[124:125]
	v_cvt_pk_bf16_f32 v112, v112, v113
	v_cvt_pk_bf16_f32 v113, v114, v115
	v_cvt_pk_bf16_f32 v114, v116, v117
	v_cvt_pk_bf16_f32 v115, v118, v119
	global_store_dwordx4 v[226:227], v[112:115], off offset:64
	v_pk_add_f32 v[120:121], v[120:121], v[122:123]
	s_nop 0
	v_add_f32_e32 v120, v120, v121
	v_add_f32_e32 v213, v120, v213
.LBB0_1605:
	s_or_b64 exec, exec, s[0:1]
	v_and_b32_e32 v113, 64, v233
	v_xor_b32_e32 v112, 16, v233
	v_add_u32_e32 v113, 64, v113
	v_cmp_lt_i32_e64 s[0:1], v112, v113
	v_xor_b32_e32 v114, 32, v233
	s_and_b64 s[14:15], s[6:7], s[14:15]
	v_cndmask_b32_e64 v112, v233, v112, s[0:1]
	s_waitcnt vmcnt(6)
	v_lshlrev_b32_e32 v176, 2, v112
	ds_bpermute_b32 v112, v176, v213
	v_cmp_lt_i32_e64 s[0:1], v114, v113
	s_waitcnt lgkmcnt(0)
	v_add_f32_e32 v112, v213, v112
	v_cndmask_b32_e64 v113, v233, v114, s[0:1]
	v_lshlrev_b32_e32 v177, 2, v113
	ds_bpermute_b32 v113, v177, v112
	s_and_saveexec_b64 s[0:1], s[14:15]
	s_cbranch_execz .LBB0_1607
	v_lshl_add_u64 v[114:115], v[206:207], 2, s[16:17]
	s_waitcnt lgkmcnt(0)
	v_add_f32_e32 v112, v112, v113
	global_atomic_add_f32 v[114:115], v112, off
